# v43 + pool phase: the re-read of the window's old rows is issued at the start of the batch (arrives under the reduction / barrier / rstd work)
# speedup vs baseline: 1.0015x; 1.0015x over previous
.Lp1f_loop:
	s_waitcnt vmcnt(16)
	s_add_i32 s52, s14, 0
	s_sub_i32 s52, s52, s12
	s_max_i32 s52, s52, 0
	s_mov_b32 s53, 0
	s_lshl_b64 s[52:53], s[52:53], 14
	s_add_u32 s52, s52, s2
	s_addc_u32 s53, s53, s3
	global_load_dwordx4 v[144:147], v1, s[52:53]
	global_load_dwordx4 v[148:151], v1, s[52:53] offset:1024
	s_add_i32 s52, s14, 1
	s_sub_i32 s52, s52, s12
	s_max_i32 s52, s52, 0
	s_mov_b32 s53, 0
	s_lshl_b64 s[52:53], s[52:53], 14
	s_add_u32 s52, s52, s2
	s_addc_u32 s53, s53, s3
	global_load_dwordx4 v[152:155], v1, s[52:53]
	global_load_dwordx4 v[156:159], v1, s[52:53] offset:1024
	s_add_i32 s52, s14, 2
	s_sub_i32 s52, s52, s12
	s_max_i32 s52, s52, 0
	s_mov_b32 s53, 0
	s_lshl_b64 s[52:53], s[52:53], 14
	s_add_u32 s52, s52, s2
	s_addc_u32 s53, s53, s3
	global_load_dwordx4 v[160:163], v1, s[52:53]
	global_load_dwordx4 v[164:167], v1, s[52:53] offset:1024
	s_add_i32 s52, s14, 3
	s_sub_i32 s52, s52, s12
	s_max_i32 s52, s52, 0
	s_mov_b32 s53, 0
	s_lshl_b64 s[52:53], s[52:53], 14
	s_add_u32 s52, s52, s2
	s_addc_u32 s53, s53, s3
	global_load_dwordx4 v[168:171], v1, s[52:53]
	global_load_dwordx4 v[172:175], v1, s[52:53] offset:1024
	s_add_i32 s52, s14, 4
	s_sub_i32 s52, s52, s12
	s_max_i32 s52, s52, 0
	s_mov_b32 s53, 0
	s_lshl_b64 s[52:53], s[52:53], 14
	s_add_u32 s52, s52, s2
	s_addc_u32 s53, s53, s3
	global_load_dwordx4 v[176:179], v1, s[52:53]
	global_load_dwordx4 v[180:183], v1, s[52:53] offset:1024
	s_add_i32 s52, s14, 5
	s_sub_i32 s52, s52, s12
	s_max_i32 s52, s52, 0
	s_mov_b32 s53, 0
	s_lshl_b64 s[52:53], s[52:53], 14
	s_add_u32 s52, s52, s2
	s_addc_u32 s53, s53, s3
	global_load_dwordx4 v[184:187], v1, s[52:53]
	global_load_dwordx4 v[188:191], v1, s[52:53] offset:1024
	s_add_i32 s52, s14, 6
	s_sub_i32 s52, s52, s12
	s_max_i32 s52, s52, 0
	s_mov_b32 s53, 0
	s_lshl_b64 s[52:53], s[52:53], 14
	s_add_u32 s52, s52, s2
	s_addc_u32 s53, s53, s3
	global_load_dwordx4 v[192:195], v1, s[52:53]
	global_load_dwordx4 v[196:199], v1, s[52:53] offset:1024
	s_add_i32 s52, s14, 7
	s_sub_i32 s52, s52, s12
	s_max_i32 s52, s52, 0
	s_mov_b32 s53, 0
	s_lshl_b64 s[52:53], s[52:53], 14
	s_add_u32 s52, s52, s2
	s_addc_u32 s53, s53, s3
	global_load_dwordx4 v[200:203], v1, s[52:53]
	global_load_dwordx4 v[204:207], v1, s[52:53] offset:1024
	v_mul_f32_e32 v80, v16, v16
	v_fmac_f32_e32 v80, v17, v17
	v_fmac_f32_e32 v80, v18, v18
	v_fmac_f32_e32 v80, v19, v19
	v_fmac_f32_e32 v80, v20, v20
	v_fmac_f32_e32 v80, v21, v21
	v_fmac_f32_e32 v80, v22, v22
	v_fmac_f32_e32 v80, v23, v23
	v_mul_f32_e32 v81, v24, v24
	v_fmac_f32_e32 v81, v25, v25
	v_fmac_f32_e32 v81, v26, v26
	v_fmac_f32_e32 v81, v27, v27
	v_fmac_f32_e32 v81, v28, v28
	v_fmac_f32_e32 v81, v29, v29
	v_fmac_f32_e32 v81, v30, v30
	v_fmac_f32_e32 v81, v31, v31
	v_mul_f32_e32 v82, v32, v32
	v_fmac_f32_e32 v82, v33, v33
	v_fmac_f32_e32 v82, v34, v34
	v_fmac_f32_e32 v82, v35, v35
	v_fmac_f32_e32 v82, v36, v36
	v_fmac_f32_e32 v82, v37, v37
	v_fmac_f32_e32 v82, v38, v38
	v_fmac_f32_e32 v82, v39, v39
	v_mul_f32_e32 v83, v40, v40
	v_fmac_f32_e32 v83, v41, v41
	v_fmac_f32_e32 v83, v42, v42
	v_fmac_f32_e32 v83, v43, v43
	v_fmac_f32_e32 v83, v44, v44
	v_fmac_f32_e32 v83, v45, v45
	v_fmac_f32_e32 v83, v46, v46
	v_fmac_f32_e32 v83, v47, v47
	v_mul_f32_e32 v84, v48, v48
	v_fmac_f32_e32 v84, v49, v49
	v_fmac_f32_e32 v84, v50, v50
	v_fmac_f32_e32 v84, v51, v51
	v_fmac_f32_e32 v84, v52, v52
	v_fmac_f32_e32 v84, v53, v53
	v_fmac_f32_e32 v84, v54, v54
	v_fmac_f32_e32 v84, v55, v55
	v_mul_f32_e32 v85, v56, v56
	v_fmac_f32_e32 v85, v57, v57
	v_fmac_f32_e32 v85, v58, v58
	v_fmac_f32_e32 v85, v59, v59
	v_fmac_f32_e32 v85, v60, v60
	v_fmac_f32_e32 v85, v61, v61
	v_fmac_f32_e32 v85, v62, v62
	v_fmac_f32_e32 v85, v63, v63
	v_mul_f32_e32 v86, v64, v64
	v_fmac_f32_e32 v86, v65, v65
	v_fmac_f32_e32 v86, v66, v66
	v_fmac_f32_e32 v86, v67, v67
	v_fmac_f32_e32 v86, v68, v68
	v_fmac_f32_e32 v86, v69, v69
	v_fmac_f32_e32 v86, v70, v70
	v_fmac_f32_e32 v86, v71, v71
	v_mul_f32_e32 v87, v72, v72
	v_fmac_f32_e32 v87, v73, v73
	v_fmac_f32_e32 v87, v74, v74
	v_fmac_f32_e32 v87, v75, v75
	v_fmac_f32_e32 v87, v76, v76
	v_fmac_f32_e32 v87, v77, v77
	v_fmac_f32_e32 v87, v78, v78
	v_fmac_f32_e32 v87, v79, v79
	s_nop 1
	v_add_f32_dpp v80, v80, v80 quad_perm:[1,0,3,2] row_mask:0xf bank_mask:0xf bound_ctrl:1
	v_add_f32_dpp v81, v81, v81 quad_perm:[1,0,3,2] row_mask:0xf bank_mask:0xf bound_ctrl:1
	v_add_f32_dpp v82, v82, v82 quad_perm:[1,0,3,2] row_mask:0xf bank_mask:0xf bound_ctrl:1
	v_add_f32_dpp v83, v83, v83 quad_perm:[1,0,3,2] row_mask:0xf bank_mask:0xf bound_ctrl:1
	v_add_f32_dpp v84, v84, v84 quad_perm:[1,0,3,2] row_mask:0xf bank_mask:0xf bound_ctrl:1
	v_add_f32_dpp v85, v85, v85 quad_perm:[1,0,3,2] row_mask:0xf bank_mask:0xf bound_ctrl:1
	v_add_f32_dpp v86, v86, v86 quad_perm:[1,0,3,2] row_mask:0xf bank_mask:0xf bound_ctrl:1
	v_add_f32_dpp v87, v87, v87 quad_perm:[1,0,3,2] row_mask:0xf bank_mask:0xf bound_ctrl:1
	s_nop 1
	v_add_f32_dpp v80, v80, v80 quad_perm:[2,3,0,1] row_mask:0xf bank_mask:0xf bound_ctrl:1
	v_add_f32_dpp v81, v81, v81 quad_perm:[2,3,0,1] row_mask:0xf bank_mask:0xf bound_ctrl:1
	v_add_f32_dpp v82, v82, v82 quad_perm:[2,3,0,1] row_mask:0xf bank_mask:0xf bound_ctrl:1
	v_add_f32_dpp v83, v83, v83 quad_perm:[2,3,0,1] row_mask:0xf bank_mask:0xf bound_ctrl:1
	v_add_f32_dpp v84, v84, v84 quad_perm:[2,3,0,1] row_mask:0xf bank_mask:0xf bound_ctrl:1
	v_add_f32_dpp v85, v85, v85 quad_perm:[2,3,0,1] row_mask:0xf bank_mask:0xf bound_ctrl:1
	v_add_f32_dpp v86, v86, v86 quad_perm:[2,3,0,1] row_mask:0xf bank_mask:0xf bound_ctrl:1
	v_add_f32_dpp v87, v87, v87 quad_perm:[2,3,0,1] row_mask:0xf bank_mask:0xf bound_ctrl:1
	s_nop 1
	v_add_f32_dpp v80, v80, v80 row_half_mirror row_mask:0xf bank_mask:0xf bound_ctrl:1
	v_add_f32_dpp v81, v81, v81 row_half_mirror row_mask:0xf bank_mask:0xf bound_ctrl:1
	v_add_f32_dpp v82, v82, v82 row_half_mirror row_mask:0xf bank_mask:0xf bound_ctrl:1
	v_add_f32_dpp v83, v83, v83 row_half_mirror row_mask:0xf bank_mask:0xf bound_ctrl:1
	v_add_f32_dpp v84, v84, v84 row_half_mirror row_mask:0xf bank_mask:0xf bound_ctrl:1
	v_add_f32_dpp v85, v85, v85 row_half_mirror row_mask:0xf bank_mask:0xf bound_ctrl:1
	v_add_f32_dpp v86, v86, v86 row_half_mirror row_mask:0xf bank_mask:0xf bound_ctrl:1
	v_add_f32_dpp v87, v87, v87 row_half_mirror row_mask:0xf bank_mask:0xf bound_ctrl:1
	s_nop 1
	v_add_f32_dpp v80, v80, v80 row_mirror row_mask:0xf bank_mask:0xf bound_ctrl:1
	v_add_f32_dpp v81, v81, v81 row_mirror row_mask:0xf bank_mask:0xf bound_ctrl:1
	v_add_f32_dpp v82, v82, v82 row_mirror row_mask:0xf bank_mask:0xf bound_ctrl:1
	v_add_f32_dpp v83, v83, v83 row_mirror row_mask:0xf bank_mask:0xf bound_ctrl:1
	v_add_f32_dpp v84, v84, v84 row_mirror row_mask:0xf bank_mask:0xf bound_ctrl:1
	v_add_f32_dpp v85, v85, v85 row_mirror row_mask:0xf bank_mask:0xf bound_ctrl:1
	v_add_f32_dpp v86, v86, v86 row_mirror row_mask:0xf bank_mask:0xf bound_ctrl:1
	v_add_f32_dpp v87, v87, v87 row_mirror row_mask:0xf bank_mask:0xf bound_ctrl:1
	v_lshrrev_b32_e32 v12, 6, v1
	v_and_b32_e32 v12, 12, v12
	s_lshl_b32 s52, s9, 4
	s_add_i32 s52, s52, 0
	v_add_u32_e32 v12, s52, v12
	s_mov_b32 exec_lo, 0x10001
	s_mov_b32 exec_hi, 0x10001
	ds_write_b32 v12, v80
	ds_write_b32 v12, v81 offset:128
	ds_write_b32 v12, v82 offset:256
	ds_write_b32 v12, v83 offset:384
	ds_write_b32 v12, v84 offset:512
	ds_write_b32 v12, v85 offset:640
	ds_write_b32 v12, v86 offset:768
	ds_write_b32 v12, v87 offset:896
	s_mov_b64 exec, -1
	s_waitcnt lgkmcnt(0)
	s_barrier
	v_lshrrev_b32_e32 v13, 4, v1
	v_and_b32_e32 v13, 7, v13
	v_lshlrev_b32_e32 v12, 7, v13
	ds_read_b128 v[88:91], v12
	ds_read_b128 v[92:95], v12 offset:16
	ds_read_b128 v[96:99], v12 offset:32
	ds_read_b128 v[100:103], v12 offset:48
	ds_read_b128 v[104:107], v12 offset:64
	ds_read_b128 v[108:111], v12 offset:80
	ds_read_b128 v[112:115], v12 offset:96
	ds_read_b128 v[116:119], v12 offset:112
	s_waitcnt lgkmcnt(0)
	v_add_f32_e32 v14, v88, v89
	v_add_f32_e32 v14, v14, v90
	v_add_f32_e32 v14, v14, v91
	v_add_f32_e32 v14, v14, v92
	v_add_f32_e32 v14, v14, v93
	v_add_f32_e32 v14, v14, v94
	v_add_f32_e32 v14, v14, v95
	v_add_f32_e32 v14, v14, v96
	v_add_f32_e32 v14, v14, v97
	v_add_f32_e32 v14, v14, v98
	v_add_f32_e32 v14, v14, v99
	v_add_f32_e32 v14, v14, v100
	v_add_f32_e32 v14, v14, v101
	v_add_f32_e32 v14, v14, v102
	v_add_f32_e32 v14, v14, v103
	v_add_f32_e32 v14, v14, v104
	v_add_f32_e32 v14, v14, v105
	v_add_f32_e32 v14, v14, v106
	v_add_f32_e32 v14, v14, v107
	v_add_f32_e32 v14, v14, v108
	v_add_f32_e32 v14, v14, v109
	v_add_f32_e32 v14, v14, v110
	v_add_f32_e32 v14, v14, v111
	v_add_f32_e32 v14, v14, v112
	v_add_f32_e32 v14, v14, v113
	v_add_f32_e32 v14, v14, v114
	v_add_f32_e32 v14, v14, v115
	v_add_f32_e32 v14, v14, v116
	v_add_f32_e32 v14, v14, v117
	v_add_f32_e32 v14, v14, v118
	v_add_f32_e32 v14, v14, v119
	v_mov_b32_e32 v221, 0x358637bd
	v_mov_b32_e32 v222, 0x260
	s_mov_b32 s54, 0xf800000
	v_fmamk_f32 v14, v14, 0x39800000, v221
	v_mul_f32_e32 v15, 0x4f800000, v14
	v_cmp_gt_f32_e32 vcc, s54, v14
	s_nop 1
	v_cndmask_b32_e32 v14, v14, v15, vcc
	v_sqrt_f32_e32 v15, v14
	s_nop 0
	v_add_u32_e32 v216, -1, v15
	v_add_u32_e32 v217, 1, v15
	v_fma_f32 v218, -v216, v15, v14
	v_fma_f32 v220, -v217, v15, v14
	v_cmp_ge_f32_e64 s[30:31], 0, v218
	s_nop 1
	v_cndmask_b32_e64 v15, v15, v216, s[30:31]
	v_cmp_lt_f32_e64 s[30:31], 0, v220
	s_nop 1
	v_cndmask_b32_e64 v15, v15, v217, s[30:31]
	v_mul_f32_e32 v216, 0x37800000, v15
	v_cndmask_b32_e32 v15, v15, v216, vcc
	v_cmp_class_f32_e32 vcc, v14, v222
	s_nop 1
	v_cndmask_b32_e32 v14, v15, v14, vcc
	v_div_scale_f32 v15, s[30:31], v14, v14, 1.0
	v_rcp_f32_e32 v216, v15
	v_div_scale_f32 v217, vcc, 1.0, v14, 1.0
	v_fma_f32 v218, -v15, v216, 1.0
	v_fmac_f32_e32 v216, v218, v216
	v_mul_f32_e32 v218, v217, v216
	v_fma_f32 v220, -v15, v218, v217
	v_fmac_f32_e32 v218, v220, v216
	v_fma_f32 v15, -v15, v218, v217
	v_div_fmas_f32 v15, v15, v216, v218
	v_div_fixup_f32 v14, v15, v14, 1.0
	s_mul_i32 s52, s9, 320
	s_lshl_b32 s53, s13, 5
	s_add_i32 s52, s52, s53
	s_add_i32 s52, s52, 0x800
	v_lshl_add_u32 v12, v13, 2, s52
	ds_write_b32 v12, v14
	s_nop 1
	v_readlane_b32 s20, v14, 0
	v_readlane_b32 s21, v14, 1
	v_readlane_b32 s22, v14, 2
	v_readlane_b32 s23, v14, 3
	v_readlane_b32 s24, v14, 4
	v_readlane_b32 s25, v14, 5
	v_readlane_b32 s26, v14, 6
	v_readlane_b32 s27, v14, 7
	s_lshl_b32 s53, s12, 2
	v_subrev_u32_e32 v216, s53, v12
	ds_read_b32 v217, v216
	v_add_u32_e32 v218, s15, v13
	v_cmp_le_u32_e32 vcc, s12, v218
	v_add_u32_e32 v218, 1, v218
	v_min_u32_e32 v218, s12, v218
	v_cvt_f32_u32_e32 v220, v218
	s_waitcnt lgkmcnt(0)
	v_cndmask_b32_e32 v217, 0, v217, vcc
	s_nop 1
	v_readlane_b32 s36, v217, 0
	v_readlane_b32 s37, v217, 1
	v_readlane_b32 s38, v217, 2
	v_readlane_b32 s39, v217, 3
	v_readlane_b32 s40, v217, 4
	v_readlane_b32 s41, v217, 5
	v_readlane_b32 s42, v217, 6
	v_readlane_b32 s43, v217, 7
	v_div_scale_f32 v15, s[30:31], v220, v220, 1.0
	v_rcp_f32_e32 v216, v15
	v_div_scale_f32 v217, vcc, 1.0, v220, 1.0
	v_fma_f32 v218, -v15, v216, 1.0
	v_fmac_f32_e32 v216, v218, v216
	v_mul_f32_e32 v218, v217, v216
	v_fma_f32 v221, -v15, v218, v217
	v_fmac_f32_e32 v218, v221, v216
	v_fma_f32 v15, -v15, v218, v217
	v_div_fmas_f32 v15, v15, v216, v218
	v_div_fixup_f32 v14, v15, v220, 1.0
	s_nop 1
	v_readlane_b32 s44, v14, 0
	v_readlane_b32 s45, v14, 1
	v_readlane_b32 s46, v14, 2
	v_readlane_b32 s47, v14, 3
	v_readlane_b32 s48, v14, 4
	v_readlane_b32 s49, v14, 5
	v_readlane_b32 s50, v14, 6
	v_readlane_b32 s51, v14, 7
	s_nop 1
	s_cmp_ge_u32 s13, 9
	s_cbranch_scc1 .Lp1f_nonext_m0
	s_add_i32 s55, s14, 8
	s_add_i32 s52, s55, 0
	s_mov_b32 s53, 0
	s_lshl_b64 s[52:53], s[52:53], 14
	s_add_u32 s52, s52, s2
	s_addc_u32 s53, s53, s3
	global_load_dwordx4 v[80:83], v1, s[52:53]
	global_load_dwordx4 v[84:87], v1, s[52:53] offset:1024
	s_add_i32 s52, s55, 1
	s_mov_b32 s53, 0
	s_lshl_b64 s[52:53], s[52:53], 14
	s_add_u32 s52, s52, s2
	s_addc_u32 s53, s53, s3
	global_load_dwordx4 v[88:91], v1, s[52:53]
	global_load_dwordx4 v[92:95], v1, s[52:53] offset:1024
	s_add_i32 s52, s55, 2
	s_mov_b32 s53, 0
	s_lshl_b64 s[52:53], s[52:53], 14
	s_add_u32 s52, s52, s2
	s_addc_u32 s53, s53, s3
	global_load_dwordx4 v[96:99], v1, s[52:53]
	global_load_dwordx4 v[100:103], v1, s[52:53] offset:1024
	s_add_i32 s52, s55, 3
	s_mov_b32 s53, 0
	s_lshl_b64 s[52:53], s[52:53], 14
	s_add_u32 s52, s52, s2
	s_addc_u32 s53, s53, s3
	global_load_dwordx4 v[104:107], v1, s[52:53]
	global_load_dwordx4 v[108:111], v1, s[52:53] offset:1024
	s_add_i32 s52, s55, 4
	s_mov_b32 s53, 0
	s_lshl_b64 s[52:53], s[52:53], 14
	s_add_u32 s52, s52, s2
	s_addc_u32 s53, s53, s3
	global_load_dwordx4 v[112:115], v1, s[52:53]
	global_load_dwordx4 v[116:119], v1, s[52:53] offset:1024
	s_add_i32 s52, s55, 5
	s_mov_b32 s53, 0
	s_lshl_b64 s[52:53], s[52:53], 14
	s_add_u32 s52, s52, s2
	s_addc_u32 s53, s53, s3
	global_load_dwordx4 v[120:123], v1, s[52:53]
	global_load_dwordx4 v[124:127], v1, s[52:53] offset:1024
	s_add_i32 s52, s55, 6
	s_mov_b32 s53, 0
	s_lshl_b64 s[52:53], s[52:53], 14
	s_add_u32 s52, s52, s2
	s_addc_u32 s53, s53, s3
	global_load_dwordx4 v[128:131], v1, s[52:53]
	global_load_dwordx4 v[132:135], v1, s[52:53] offset:1024
	s_add_i32 s52, s55, 7
	s_mov_b32 s53, 0
	s_lshl_b64 s[52:53], s[52:53], 14
	s_add_u32 s52, s52, s2
	s_addc_u32 s53, s53, s3
	global_load_dwordx4 v[136:139], v1, s[52:53]
	global_load_dwordx4 v[140:143], v1, s[52:53] offset:1024

.Lp1f_w1_m0:
	v_mul_f32_e32 v144, s36, v144
	v_mul_f32_e32 v145, s36, v145
	v_mul_f32_e32 v146, s36, v146
	v_mul_f32_e32 v147, s36, v147
	v_mul_f32_e32 v148, s36, v148
	v_mul_f32_e32 v149, s36, v149
	v_mul_f32_e32 v150, s36, v150
	v_mul_f32_e32 v151, s36, v151
	v_pk_mul_f32 v[144:145], v[144:145], v[4:5]
	v_pk_mul_f32 v[146:147], v[146:147], v[6:7]
	v_pk_mul_f32 v[148:149], v[148:149], v[8:9]
	v_pk_mul_f32 v[150:151], v[150:151], v[10:11]
	v_mul_f32_e32 v152, s37, v152
	v_mul_f32_e32 v153, s37, v153
	v_mul_f32_e32 v154, s37, v154
	v_mul_f32_e32 v155, s37, v155
	v_mul_f32_e32 v156, s37, v156
	v_mul_f32_e32 v157, s37, v157
	v_mul_f32_e32 v158, s37, v158
	v_mul_f32_e32 v159, s37, v159
	v_pk_mul_f32 v[152:153], v[152:153], v[4:5]
	v_pk_mul_f32 v[154:155], v[154:155], v[6:7]
	v_pk_mul_f32 v[156:157], v[156:157], v[8:9]
	v_pk_mul_f32 v[158:159], v[158:159], v[10:11]
	v_mul_f32_e32 v160, s38, v160
	v_mul_f32_e32 v161, s38, v161
	v_mul_f32_e32 v162, s38, v162
	v_mul_f32_e32 v163, s38, v163
	v_mul_f32_e32 v164, s38, v164
	v_mul_f32_e32 v165, s38, v165
	v_mul_f32_e32 v166, s38, v166
	v_mul_f32_e32 v167, s38, v167
	v_pk_mul_f32 v[160:161], v[160:161], v[4:5]
	v_pk_mul_f32 v[162:163], v[162:163], v[6:7]
	v_pk_mul_f32 v[164:165], v[164:165], v[8:9]
	v_pk_mul_f32 v[166:167], v[166:167], v[10:11]
	v_mul_f32_e32 v168, s39, v168
	v_mul_f32_e32 v169, s39, v169
	v_mul_f32_e32 v170, s39, v170
	v_mul_f32_e32 v171, s39, v171
	v_mul_f32_e32 v172, s39, v172
	v_mul_f32_e32 v173, s39, v173
	v_mul_f32_e32 v174, s39, v174
	v_mul_f32_e32 v175, s39, v175
	v_pk_mul_f32 v[168:169], v[168:169], v[4:5]
	v_pk_mul_f32 v[170:171], v[170:171], v[6:7]
	v_pk_mul_f32 v[172:173], v[172:173], v[8:9]
	v_pk_mul_f32 v[174:175], v[174:175], v[10:11]
	v_mul_f32_e32 v176, s40, v176
	v_mul_f32_e32 v177, s40, v177
	v_mul_f32_e32 v178, s40, v178
	v_mul_f32_e32 v179, s40, v179
	v_mul_f32_e32 v180, s40, v180
	v_mul_f32_e32 v181, s40, v181
	v_mul_f32_e32 v182, s40, v182
	v_mul_f32_e32 v183, s40, v183
	v_pk_mul_f32 v[176:177], v[176:177], v[4:5]
	v_pk_mul_f32 v[178:179], v[178:179], v[6:7]
	v_pk_mul_f32 v[180:181], v[180:181], v[8:9]
	v_pk_mul_f32 v[182:183], v[182:183], v[10:11]
	v_mul_f32_e32 v184, s41, v184
	v_mul_f32_e32 v185, s41, v185
	v_mul_f32_e32 v186, s41, v186
	v_mul_f32_e32 v187, s41, v187
	v_mul_f32_e32 v188, s41, v188
	v_mul_f32_e32 v189, s41, v189
	v_mul_f32_e32 v190, s41, v190
	v_mul_f32_e32 v191, s41, v191
	v_pk_mul_f32 v[184:185], v[184:185], v[4:5]
	v_pk_mul_f32 v[186:187], v[186:187], v[6:7]
	v_pk_mul_f32 v[188:189], v[188:189], v[8:9]
	v_pk_mul_f32 v[190:191], v[190:191], v[10:11]
	v_mul_f32_e32 v192, s42, v192
	v_mul_f32_e32 v193, s42, v193
	v_mul_f32_e32 v194, s42, v194
	v_mul_f32_e32 v195, s42, v195
	v_mul_f32_e32 v196, s42, v196
	v_mul_f32_e32 v197, s42, v197
	v_mul_f32_e32 v198, s42, v198
	v_mul_f32_e32 v199, s42, v199
	v_pk_mul_f32 v[192:193], v[192:193], v[4:5]
	v_pk_mul_f32 v[194:195], v[194:195], v[6:7]
	v_pk_mul_f32 v[196:197], v[196:197], v[8:9]
	v_pk_mul_f32 v[198:199], v[198:199], v[10:11]
	v_mul_f32_e32 v200, s43, v200
	v_mul_f32_e32 v201, s43, v201
	v_mul_f32_e32 v202, s43, v202
	v_mul_f32_e32 v203, s43, v203
	v_mul_f32_e32 v204, s43, v204
	v_mul_f32_e32 v205, s43, v205
	v_mul_f32_e32 v206, s43, v206
	v_mul_f32_e32 v207, s43, v207
	v_pk_mul_f32 v[200:201], v[200:201], v[4:5]
	v_pk_mul_f32 v[202:203], v[202:203], v[6:7]
	v_pk_mul_f32 v[204:205], v[204:205], v[8:9]
	v_pk_mul_f32 v[206:207], v[206:207], v[10:11]
	v_pk_add_f32 v[208:209], v[208:209], v[16:17]
	v_pk_add_f32 v[210:211], v[210:211], v[18:19]
	v_pk_add_f32 v[212:213], v[212:213], v[20:21]
	v_pk_add_f32 v[214:215], v[214:215], v[22:23]
	v_pk_add_f32 v[208:209], v[208:209], v[144:145] neg_lo:[0,1] neg_hi:[0,1]
	v_pk_add_f32 v[210:211], v[210:211], v[146:147] neg_lo:[0,1] neg_hi:[0,1]
	v_pk_add_f32 v[212:213], v[212:213], v[148:149] neg_lo:[0,1] neg_hi:[0,1]
	v_pk_add_f32 v[214:215], v[214:215], v[150:151] neg_lo:[0,1] neg_hi:[0,1]
	v_fma_f32 v12, v208, s44, -v16
	v_fma_f32 v13, v209, s44, -v17
	v_fma_f32 v14, v210, s44, -v18
	v_fma_f32 v15, v211, s44, -v19
	v_fma_f32 v216, v212, s44, -v20
	v_fma_f32 v217, v213, s44, -v21
	v_fma_f32 v218, v214, s44, -v22
	v_fma_f32 v220, v215, s44, -v23
	v_cvt_pk_bf16_f32 v144, v12, v13
	v_cvt_pk_bf16_f32 v145, v14, v15
	v_cvt_pk_bf16_f32 v146, v216, v217
	v_cvt_pk_bf16_f32 v147, v218, v220
	s_add_i32 s52, s14, 0
	s_mov_b32 s53, 0
	s_lshl_b64 s[52:53], s[52:53], 13
	s_add_u32 s52, s52, s4
	s_addc_u32 s53, s53, s5
	global_store_dwordx2 v3, v[144:145], s[52:53]
	global_store_dwordx2 v3, v[146:147], s[52:53] offset:512
	v_pk_add_f32 v[208:209], v[208:209], v[24:25]
	v_pk_add_f32 v[210:211], v[210:211], v[26:27]
	v_pk_add_f32 v[212:213], v[212:213], v[28:29]
	v_pk_add_f32 v[214:215], v[214:215], v[30:31]
	v_pk_add_f32 v[208:209], v[208:209], v[152:153] neg_lo:[0,1] neg_hi:[0,1]
	v_pk_add_f32 v[210:211], v[210:211], v[154:155] neg_lo:[0,1] neg_hi:[0,1]
	v_pk_add_f32 v[212:213], v[212:213], v[156:157] neg_lo:[0,1] neg_hi:[0,1]
	v_pk_add_f32 v[214:215], v[214:215], v[158:159] neg_lo:[0,1] neg_hi:[0,1]
	v_fma_f32 v12, v208, s45, -v24
	v_fma_f32 v13, v209, s45, -v25
	v_fma_f32 v14, v210, s45, -v26
	v_fma_f32 v15, v211, s45, -v27
	v_fma_f32 v216, v212, s45, -v28
	v_fma_f32 v217, v213, s45, -v29
	v_fma_f32 v218, v214, s45, -v30
	v_fma_f32 v220, v215, s45, -v31
	v_cvt_pk_bf16_f32 v152, v12, v13
	v_cvt_pk_bf16_f32 v153, v14, v15
	v_cvt_pk_bf16_f32 v154, v216, v217
	v_cvt_pk_bf16_f32 v155, v218, v220
	s_add_i32 s52, s14, 1
	s_mov_b32 s53, 0
	s_lshl_b64 s[52:53], s[52:53], 13
	s_add_u32 s52, s52, s4
	s_addc_u32 s53, s53, s5
	global_store_dwordx2 v3, v[152:153], s[52:53]
	global_store_dwordx2 v3, v[154:155], s[52:53] offset:512
	v_pk_add_f32 v[208:209], v[208:209], v[32:33]
	v_pk_add_f32 v[210:211], v[210:211], v[34:35]
	v_pk_add_f32 v[212:213], v[212:213], v[36:37]
	v_pk_add_f32 v[214:215], v[214:215], v[38:39]
	v_pk_add_f32 v[208:209], v[208:209], v[160:161] neg_lo:[0,1] neg_hi:[0,1]
	v_pk_add_f32 v[210:211], v[210:211], v[162:163] neg_lo:[0,1] neg_hi:[0,1]
	v_pk_add_f32 v[212:213], v[212:213], v[164:165] neg_lo:[0,1] neg_hi:[0,1]
	v_pk_add_f32 v[214:215], v[214:215], v[166:167] neg_lo:[0,1] neg_hi:[0,1]
	v_fma_f32 v12, v208, s46, -v32
	v_fma_f32 v13, v209, s46, -v33
	v_fma_f32 v14, v210, s46, -v34
	v_fma_f32 v15, v211, s46, -v35
	v_fma_f32 v216, v212, s46, -v36
	v_fma_f32 v217, v213, s46, -v37
	v_fma_f32 v218, v214, s46, -v38
	v_fma_f32 v220, v215, s46, -v39
	v_cvt_pk_bf16_f32 v160, v12, v13
	v_cvt_pk_bf16_f32 v161, v14, v15
	v_cvt_pk_bf16_f32 v162, v216, v217
	v_cvt_pk_bf16_f32 v163, v218, v220
	s_add_i32 s52, s14, 2
	s_mov_b32 s53, 0
	s_lshl_b64 s[52:53], s[52:53], 13
	s_add_u32 s52, s52, s4
	s_addc_u32 s53, s53, s5
	global_store_dwordx2 v3, v[160:161], s[52:53]
	global_store_dwordx2 v3, v[162:163], s[52:53] offset:512
	v_pk_add_f32 v[208:209], v[208:209], v[40:41]
	v_pk_add_f32 v[210:211], v[210:211], v[42:43]
	v_pk_add_f32 v[212:213], v[212:213], v[44:45]
	v_pk_add_f32 v[214:215], v[214:215], v[46:47]
	v_pk_add_f32 v[208:209], v[208:209], v[168:169] neg_lo:[0,1] neg_hi:[0,1]
	v_pk_add_f32 v[210:211], v[210:211], v[170:171] neg_lo:[0,1] neg_hi:[0,1]
	v_pk_add_f32 v[212:213], v[212:213], v[172:173] neg_lo:[0,1] neg_hi:[0,1]
	v_pk_add_f32 v[214:215], v[214:215], v[174:175] neg_lo:[0,1] neg_hi:[0,1]
	v_fma_f32 v12, v208, s47, -v40
	v_fma_f32 v13, v209, s47, -v41
	v_fma_f32 v14, v210, s47, -v42
	v_fma_f32 v15, v211, s47, -v43
	v_fma_f32 v216, v212, s47, -v44
	v_fma_f32 v217, v213, s47, -v45
	v_fma_f32 v218, v214, s47, -v46
	v_fma_f32 v220, v215, s47, -v47
	v_cvt_pk_bf16_f32 v168, v12, v13
	v_cvt_pk_bf16_f32 v169, v14, v15
	v_cvt_pk_bf16_f32 v170, v216, v217
	v_cvt_pk_bf16_f32 v171, v218, v220
	s_add_i32 s52, s14, 3
	s_mov_b32 s53, 0
	s_lshl_b64 s[52:53], s[52:53], 13
	s_add_u32 s52, s52, s4
	s_addc_u32 s53, s53, s5
	global_store_dwordx2 v3, v[168:169], s[52:53]
	global_store_dwordx2 v3, v[170:171], s[52:53] offset:512
	v_pk_add_f32 v[208:209], v[208:209], v[48:49]
	v_pk_add_f32 v[210:211], v[210:211], v[50:51]
	v_pk_add_f32 v[212:213], v[212:213], v[52:53]
	v_pk_add_f32 v[214:215], v[214:215], v[54:55]
	v_pk_add_f32 v[208:209], v[208:209], v[176:177] neg_lo:[0,1] neg_hi:[0,1]
	v_pk_add_f32 v[210:211], v[210:211], v[178:179] neg_lo:[0,1] neg_hi:[0,1]
	v_pk_add_f32 v[212:213], v[212:213], v[180:181] neg_lo:[0,1] neg_hi:[0,1]
	v_pk_add_f32 v[214:215], v[214:215], v[182:183] neg_lo:[0,1] neg_hi:[0,1]
	v_fma_f32 v12, v208, s48, -v48
	v_fma_f32 v13, v209, s48, -v49
	v_fma_f32 v14, v210, s48, -v50
	v_fma_f32 v15, v211, s48, -v51
	v_fma_f32 v216, v212, s48, -v52
	v_fma_f32 v217, v213, s48, -v53
	v_fma_f32 v218, v214, s48, -v54
	v_fma_f32 v220, v215, s48, -v55
	v_cvt_pk_bf16_f32 v176, v12, v13
	v_cvt_pk_bf16_f32 v177, v14, v15
	v_cvt_pk_bf16_f32 v178, v216, v217
	v_cvt_pk_bf16_f32 v179, v218, v220
	s_add_i32 s52, s14, 4
	s_mov_b32 s53, 0
	s_lshl_b64 s[52:53], s[52:53], 13
	s_add_u32 s52, s52, s4
	s_addc_u32 s53, s53, s5
	global_store_dwordx2 v3, v[176:177], s[52:53]
	global_store_dwordx2 v3, v[178:179], s[52:53] offset:512
	v_pk_add_f32 v[208:209], v[208:209], v[56:57]
	v_pk_add_f32 v[210:211], v[210:211], v[58:59]
	v_pk_add_f32 v[212:213], v[212:213], v[60:61]
	v_pk_add_f32 v[214:215], v[214:215], v[62:63]
	v_pk_add_f32 v[208:209], v[208:209], v[184:185] neg_lo:[0,1] neg_hi:[0,1]
	v_pk_add_f32 v[210:211], v[210:211], v[186:187] neg_lo:[0,1] neg_hi:[0,1]
	v_pk_add_f32 v[212:213], v[212:213], v[188:189] neg_lo:[0,1] neg_hi:[0,1]
	v_pk_add_f32 v[214:215], v[214:215], v[190:191] neg_lo:[0,1] neg_hi:[0,1]
	v_fma_f32 v12, v208, s49, -v56
	v_fma_f32 v13, v209, s49, -v57
	v_fma_f32 v14, v210, s49, -v58
	v_fma_f32 v15, v211, s49, -v59
	v_fma_f32 v216, v212, s49, -v60
	v_fma_f32 v217, v213, s49, -v61
	v_fma_f32 v218, v214, s49, -v62
	v_fma_f32 v220, v215, s49, -v63
	v_cvt_pk_bf16_f32 v184, v12, v13
	v_cvt_pk_bf16_f32 v185, v14, v15
	v_cvt_pk_bf16_f32 v186, v216, v217
	v_cvt_pk_bf16_f32 v187, v218, v220
	s_add_i32 s52, s14, 5
	s_mov_b32 s53, 0
	s_lshl_b64 s[52:53], s[52:53], 13
	s_add_u32 s52, s52, s4
	s_addc_u32 s53, s53, s5
	global_store_dwordx2 v3, v[184:185], s[52:53]
	global_store_dwordx2 v3, v[186:187], s[52:53] offset:512
	v_pk_add_f32 v[208:209], v[208:209], v[64:65]
	v_pk_add_f32 v[210:211], v[210:211], v[66:67]
	v_pk_add_f32 v[212:213], v[212:213], v[68:69]
	v_pk_add_f32 v[214:215], v[214:215], v[70:71]
	v_pk_add_f32 v[208:209], v[208:209], v[192:193] neg_lo:[0,1] neg_hi:[0,1]
	v_pk_add_f32 v[210:211], v[210:211], v[194:195] neg_lo:[0,1] neg_hi:[0,1]
	v_pk_add_f32 v[212:213], v[212:213], v[196:197] neg_lo:[0,1] neg_hi:[0,1]
	v_pk_add_f32 v[214:215], v[214:215], v[198:199] neg_lo:[0,1] neg_hi:[0,1]
	v_fma_f32 v12, v208, s50, -v64
	v_fma_f32 v13, v209, s50, -v65
	v_fma_f32 v14, v210, s50, -v66
	v_fma_f32 v15, v211, s50, -v67
	v_fma_f32 v216, v212, s50, -v68
	v_fma_f32 v217, v213, s50, -v69
	v_fma_f32 v218, v214, s50, -v70
	v_fma_f32 v220, v215, s50, -v71
	v_cvt_pk_bf16_f32 v192, v12, v13
	v_cvt_pk_bf16_f32 v193, v14, v15
	v_cvt_pk_bf16_f32 v194, v216, v217
	v_cvt_pk_bf16_f32 v195, v218, v220
	s_add_i32 s52, s14, 6
	s_mov_b32 s53, 0
	s_lshl_b64 s[52:53], s[52:53], 13
	s_add_u32 s52, s52, s4
	s_addc_u32 s53, s53, s5
	global_store_dwordx2 v3, v[192:193], s[52:53]
	global_store_dwordx2 v3, v[194:195], s[52:53] offset:512
	v_pk_add_f32 v[208:209], v[208:209], v[72:73]
	v_pk_add_f32 v[210:211], v[210:211], v[74:75]
	v_pk_add_f32 v[212:213], v[212:213], v[76:77]
	v_pk_add_f32 v[214:215], v[214:215], v[78:79]
	v_pk_add_f32 v[208:209], v[208:209], v[200:201] neg_lo:[0,1] neg_hi:[0,1]
	v_pk_add_f32 v[210:211], v[210:211], v[202:203] neg_lo:[0,1] neg_hi:[0,1]
	v_pk_add_f32 v[212:213], v[212:213], v[204:205] neg_lo:[0,1] neg_hi:[0,1]
	v_pk_add_f32 v[214:215], v[214:215], v[206:207] neg_lo:[0,1] neg_hi:[0,1]
	v_fma_f32 v12, v208, s51, -v72
	v_fma_f32 v13, v209, s51, -v73
	v_fma_f32 v14, v210, s51, -v74
	v_fma_f32 v15, v211, s51, -v75
	v_fma_f32 v216, v212, s51, -v76
	v_fma_f32 v217, v213, s51, -v77
	v_fma_f32 v218, v214, s51, -v78
	v_fma_f32 v220, v215, s51, -v79
	v_cvt_pk_bf16_f32 v200, v12, v13
	v_cvt_pk_bf16_f32 v201, v14, v15
	v_cvt_pk_bf16_f32 v202, v216, v217
	v_cvt_pk_bf16_f32 v203, v218, v220
	s_add_i32 s52, s14, 7
	s_mov_b32 s53, 0
	s_lshl_b64 s[52:53], s[52:53], 13
	s_add_u32 s52, s52, s4
	s_addc_u32 s53, s53, s5
	global_store_dwordx2 v3, v[200:201], s[52:53]
	global_store_dwordx2 v3, v[202:203], s[52:53] offset:512
	s_add_i32 s13, s13, 1
	s_add_i32 s14, s14, 8
	s_add_i32 s15, s15, 8
	s_waitcnt vmcnt(16)
	s_add_i32 s52, s14, 0
	s_sub_i32 s52, s52, s12
	s_max_i32 s52, s52, 0
	s_mov_b32 s53, 0
	s_lshl_b64 s[52:53], s[52:53], 14
	s_add_u32 s52, s52, s2
	s_addc_u32 s53, s53, s3
	global_load_dwordx4 v[144:147], v1, s[52:53]
	global_load_dwordx4 v[148:151], v1, s[52:53] offset:1024
	s_add_i32 s52, s14, 1
	s_sub_i32 s52, s52, s12
	s_max_i32 s52, s52, 0
	s_mov_b32 s53, 0
	s_lshl_b64 s[52:53], s[52:53], 14
	s_add_u32 s52, s52, s2
	s_addc_u32 s53, s53, s3
	global_load_dwordx4 v[152:155], v1, s[52:53]
	global_load_dwordx4 v[156:159], v1, s[52:53] offset:1024
	s_add_i32 s52, s14, 2
	s_sub_i32 s52, s52, s12
	s_max_i32 s52, s52, 0
	s_mov_b32 s53, 0
	s_lshl_b64 s[52:53], s[52:53], 14
	s_add_u32 s52, s52, s2
	s_addc_u32 s53, s53, s3
	global_load_dwordx4 v[160:163], v1, s[52:53]
	global_load_dwordx4 v[164:167], v1, s[52:53] offset:1024
	s_add_i32 s52, s14, 3
	s_sub_i32 s52, s52, s12
	s_max_i32 s52, s52, 0
	s_mov_b32 s53, 0
	s_lshl_b64 s[52:53], s[52:53], 14
	s_add_u32 s52, s52, s2
	s_addc_u32 s53, s53, s3
	global_load_dwordx4 v[168:171], v1, s[52:53]
	global_load_dwordx4 v[172:175], v1, s[52:53] offset:1024
	s_add_i32 s52, s14, 4
	s_sub_i32 s52, s52, s12
	s_max_i32 s52, s52, 0
	s_mov_b32 s53, 0
	s_lshl_b64 s[52:53], s[52:53], 14
	s_add_u32 s52, s52, s2
	s_addc_u32 s53, s53, s3
	global_load_dwordx4 v[176:179], v1, s[52:53]
	global_load_dwordx4 v[180:183], v1, s[52:53] offset:1024
	s_add_i32 s52, s14, 5
	s_sub_i32 s52, s52, s12
	s_max_i32 s52, s52, 0
	s_mov_b32 s53, 0
	s_lshl_b64 s[52:53], s[52:53], 14
	s_add_u32 s52, s52, s2
	s_addc_u32 s53, s53, s3
	global_load_dwordx4 v[184:187], v1, s[52:53]
	global_load_dwordx4 v[188:191], v1, s[52:53] offset:1024
	s_add_i32 s52, s14, 6
	s_sub_i32 s52, s52, s12
	s_max_i32 s52, s52, 0
	s_mov_b32 s53, 0
	s_lshl_b64 s[52:53], s[52:53], 14
	s_add_u32 s52, s52, s2
	s_addc_u32 s53, s53, s3
	global_load_dwordx4 v[192:195], v1, s[52:53]
	global_load_dwordx4 v[196:199], v1, s[52:53] offset:1024
	s_add_i32 s52, s14, 7
	s_sub_i32 s52, s52, s12
	s_max_i32 s52, s52, 0
	s_mov_b32 s53, 0
	s_lshl_b64 s[52:53], s[52:53], 14
	s_add_u32 s52, s52, s2
	s_addc_u32 s53, s53, s3
	global_load_dwordx4 v[200:203], v1, s[52:53]
	global_load_dwordx4 v[204:207], v1, s[52:53] offset:1024
	v_mul_f32_e32 v16, v80, v80
	v_fmac_f32_e32 v16, v81, v81
	v_fmac_f32_e32 v16, v82, v82
	v_fmac_f32_e32 v16, v83, v83
	v_fmac_f32_e32 v16, v84, v84
	v_fmac_f32_e32 v16, v85, v85
	v_fmac_f32_e32 v16, v86, v86
	v_fmac_f32_e32 v16, v87, v87
	v_mul_f32_e32 v17, v88, v88
	v_fmac_f32_e32 v17, v89, v89
	v_fmac_f32_e32 v17, v90, v90
	v_fmac_f32_e32 v17, v91, v91
	v_fmac_f32_e32 v17, v92, v92
	v_fmac_f32_e32 v17, v93, v93
	v_fmac_f32_e32 v17, v94, v94
	v_fmac_f32_e32 v17, v95, v95
	v_mul_f32_e32 v18, v96, v96
	v_fmac_f32_e32 v18, v97, v97
	v_fmac_f32_e32 v18, v98, v98
	v_fmac_f32_e32 v18, v99, v99
	v_fmac_f32_e32 v18, v100, v100
	v_fmac_f32_e32 v18, v101, v101
	v_fmac_f32_e32 v18, v102, v102
	v_fmac_f32_e32 v18, v103, v103
	v_mul_f32_e32 v19, v104, v104
	v_fmac_f32_e32 v19, v105, v105
	v_fmac_f32_e32 v19, v106, v106
	v_fmac_f32_e32 v19, v107, v107
	v_fmac_f32_e32 v19, v108, v108
	v_fmac_f32_e32 v19, v109, v109
	v_fmac_f32_e32 v19, v110, v110
	v_fmac_f32_e32 v19, v111, v111
	v_mul_f32_e32 v20, v112, v112
	v_fmac_f32_e32 v20, v113, v113
	v_fmac_f32_e32 v20, v114, v114
	v_fmac_f32_e32 v20, v115, v115
	v_fmac_f32_e32 v20, v116, v116
	v_fmac_f32_e32 v20, v117, v117
	v_fmac_f32_e32 v20, v118, v118
	v_fmac_f32_e32 v20, v119, v119
	v_mul_f32_e32 v21, v120, v120
	v_fmac_f32_e32 v21, v121, v121
	v_fmac_f32_e32 v21, v122, v122
	v_fmac_f32_e32 v21, v123, v123
	v_fmac_f32_e32 v21, v124, v124
	v_fmac_f32_e32 v21, v125, v125
	v_fmac_f32_e32 v21, v126, v126
	v_fmac_f32_e32 v21, v127, v127
	v_mul_f32_e32 v22, v128, v128
	v_fmac_f32_e32 v22, v129, v129
	v_fmac_f32_e32 v22, v130, v130
	v_fmac_f32_e32 v22, v131, v131
	v_fmac_f32_e32 v22, v132, v132
	v_fmac_f32_e32 v22, v133, v133
	v_fmac_f32_e32 v22, v134, v134
	v_fmac_f32_e32 v22, v135, v135
	v_mul_f32_e32 v23, v136, v136
	v_fmac_f32_e32 v23, v137, v137
	v_fmac_f32_e32 v23, v138, v138
	v_fmac_f32_e32 v23, v139, v139
	v_fmac_f32_e32 v23, v140, v140
	v_fmac_f32_e32 v23, v141, v141
	v_fmac_f32_e32 v23, v142, v142
	v_fmac_f32_e32 v23, v143, v143
	s_nop 1
	v_add_f32_dpp v16, v16, v16 quad_perm:[1,0,3,2] row_mask:0xf bank_mask:0xf bound_ctrl:1
	v_add_f32_dpp v17, v17, v17 quad_perm:[1,0,3,2] row_mask:0xf bank_mask:0xf bound_ctrl:1
	v_add_f32_dpp v18, v18, v18 quad_perm:[1,0,3,2] row_mask:0xf bank_mask:0xf bound_ctrl:1
	v_add_f32_dpp v19, v19, v19 quad_perm:[1,0,3,2] row_mask:0xf bank_mask:0xf bound_ctrl:1
	v_add_f32_dpp v20, v20, v20 quad_perm:[1,0,3,2] row_mask:0xf bank_mask:0xf bound_ctrl:1
	v_add_f32_dpp v21, v21, v21 quad_perm:[1,0,3,2] row_mask:0xf bank_mask:0xf bound_ctrl:1
	v_add_f32_dpp v22, v22, v22 quad_perm:[1,0,3,2] row_mask:0xf bank_mask:0xf bound_ctrl:1
	v_add_f32_dpp v23, v23, v23 quad_perm:[1,0,3,2] row_mask:0xf bank_mask:0xf bound_ctrl:1
	s_nop 1
	v_add_f32_dpp v16, v16, v16 quad_perm:[2,3,0,1] row_mask:0xf bank_mask:0xf bound_ctrl:1
	v_add_f32_dpp v17, v17, v17 quad_perm:[2,3,0,1] row_mask:0xf bank_mask:0xf bound_ctrl:1
	v_add_f32_dpp v18, v18, v18 quad_perm:[2,3,0,1] row_mask:0xf bank_mask:0xf bound_ctrl:1
	v_add_f32_dpp v19, v19, v19 quad_perm:[2,3,0,1] row_mask:0xf bank_mask:0xf bound_ctrl:1
	v_add_f32_dpp v20, v20, v20 quad_perm:[2,3,0,1] row_mask:0xf bank_mask:0xf bound_ctrl:1
	v_add_f32_dpp v21, v21, v21 quad_perm:[2,3,0,1] row_mask:0xf bank_mask:0xf bound_ctrl:1
	v_add_f32_dpp v22, v22, v22 quad_perm:[2,3,0,1] row_mask:0xf bank_mask:0xf bound_ctrl:1
	v_add_f32_dpp v23, v23, v23 quad_perm:[2,3,0,1] row_mask:0xf bank_mask:0xf bound_ctrl:1
	s_nop 1
	v_add_f32_dpp v16, v16, v16 row_half_mirror row_mask:0xf bank_mask:0xf bound_ctrl:1
	v_add_f32_dpp v17, v17, v17 row_half_mirror row_mask:0xf bank_mask:0xf bound_ctrl:1
	v_add_f32_dpp v18, v18, v18 row_half_mirror row_mask:0xf bank_mask:0xf bound_ctrl:1
	v_add_f32_dpp v19, v19, v19 row_half_mirror row_mask:0xf bank_mask:0xf bound_ctrl:1
	v_add_f32_dpp v20, v20, v20 row_half_mirror row_mask:0xf bank_mask:0xf bound_ctrl:1
	v_add_f32_dpp v21, v21, v21 row_half_mirror row_mask:0xf bank_mask:0xf bound_ctrl:1
	v_add_f32_dpp v22, v22, v22 row_half_mirror row_mask:0xf bank_mask:0xf bound_ctrl:1
	v_add_f32_dpp v23, v23, v23 row_half_mirror row_mask:0xf bank_mask:0xf bound_ctrl:1
	s_nop 1
	v_add_f32_dpp v16, v16, v16 row_mirror row_mask:0xf bank_mask:0xf bound_ctrl:1
	v_add_f32_dpp v17, v17, v17 row_mirror row_mask:0xf bank_mask:0xf bound_ctrl:1
	v_add_f32_dpp v18, v18, v18 row_mirror row_mask:0xf bank_mask:0xf bound_ctrl:1
	v_add_f32_dpp v19, v19, v19 row_mirror row_mask:0xf bank_mask:0xf bound_ctrl:1
	v_add_f32_dpp v20, v20, v20 row_mirror row_mask:0xf bank_mask:0xf bound_ctrl:1
	v_add_f32_dpp v21, v21, v21 row_mirror row_mask:0xf bank_mask:0xf bound_ctrl:1
	v_add_f32_dpp v22, v22, v22 row_mirror row_mask:0xf bank_mask:0xf bound_ctrl:1
	v_add_f32_dpp v23, v23, v23 row_mirror row_mask:0xf bank_mask:0xf bound_ctrl:1
	v_lshrrev_b32_e32 v12, 6, v1
	v_and_b32_e32 v12, 12, v12
	s_lshl_b32 s52, s9, 4
	s_add_i32 s52, s52, 1024
	v_add_u32_e32 v12, s52, v12
	s_mov_b32 exec_lo, 0x10001
	s_mov_b32 exec_hi, 0x10001
	ds_write_b32 v12, v16
	ds_write_b32 v12, v17 offset:128
	ds_write_b32 v12, v18 offset:256
	ds_write_b32 v12, v19 offset:384
	ds_write_b32 v12, v20 offset:512
	ds_write_b32 v12, v21 offset:640
	ds_write_b32 v12, v22 offset:768
	ds_write_b32 v12, v23 offset:896
	s_mov_b64 exec, -1
	s_waitcnt lgkmcnt(0)
	s_barrier
	v_lshrrev_b32_e32 v13, 4, v1
	v_and_b32_e32 v13, 7, v13
	v_lshlrev_b32_e32 v12, 7, v13
	v_add_u32_e32 v12, 0x400, v12
	ds_read_b128 v[24:27], v12
	ds_read_b128 v[28:31], v12 offset:16
	ds_read_b128 v[32:35], v12 offset:32
	ds_read_b128 v[36:39], v12 offset:48
	ds_read_b128 v[40:43], v12 offset:64
	ds_read_b128 v[44:47], v12 offset:80
	ds_read_b128 v[48:51], v12 offset:96
	ds_read_b128 v[52:55], v12 offset:112
	s_waitcnt lgkmcnt(0)
	v_add_f32_e32 v14, v24, v25
	v_add_f32_e32 v14, v14, v26
	v_add_f32_e32 v14, v14, v27
	v_add_f32_e32 v14, v14, v28
	v_add_f32_e32 v14, v14, v29
	v_add_f32_e32 v14, v14, v30
	v_add_f32_e32 v14, v14, v31
	v_add_f32_e32 v14, v14, v32
	v_add_f32_e32 v14, v14, v33
	v_add_f32_e32 v14, v14, v34
	v_add_f32_e32 v14, v14, v35
	v_add_f32_e32 v14, v14, v36
	v_add_f32_e32 v14, v14, v37
	v_add_f32_e32 v14, v14, v38
	v_add_f32_e32 v14, v14, v39
	v_add_f32_e32 v14, v14, v40
	v_add_f32_e32 v14, v14, v41
	v_add_f32_e32 v14, v14, v42
	v_add_f32_e32 v14, v14, v43
	v_add_f32_e32 v14, v14, v44
	v_add_f32_e32 v14, v14, v45
	v_add_f32_e32 v14, v14, v46
	v_add_f32_e32 v14, v14, v47
	v_add_f32_e32 v14, v14, v48
	v_add_f32_e32 v14, v14, v49
	v_add_f32_e32 v14, v14, v50
	v_add_f32_e32 v14, v14, v51
	v_add_f32_e32 v14, v14, v52
	v_add_f32_e32 v14, v14, v53
	v_add_f32_e32 v14, v14, v54
	v_add_f32_e32 v14, v14, v55
	v_mov_b32_e32 v221, 0x358637bd
	v_mov_b32_e32 v222, 0x260
	s_mov_b32 s54, 0xf800000
	v_fmamk_f32 v14, v14, 0x39800000, v221
	v_mul_f32_e32 v15, 0x4f800000, v14
	v_cmp_gt_f32_e32 vcc, s54, v14
	s_nop 1
	v_cndmask_b32_e32 v14, v14, v15, vcc
	v_sqrt_f32_e32 v15, v14
	s_nop 0
	v_add_u32_e32 v216, -1, v15
	v_add_u32_e32 v217, 1, v15
	v_fma_f32 v218, -v216, v15, v14
	v_fma_f32 v220, -v217, v15, v14
	v_cmp_ge_f32_e64 s[30:31], 0, v218
	s_nop 1
	v_cndmask_b32_e64 v15, v15, v216, s[30:31]
	v_cmp_lt_f32_e64 s[30:31], 0, v220
	s_nop 1
	v_cndmask_b32_e64 v15, v15, v217, s[30:31]
	v_mul_f32_e32 v216, 0x37800000, v15
	v_cndmask_b32_e32 v15, v15, v216, vcc
	v_cmp_class_f32_e32 vcc, v14, v222
	s_nop 1
	v_cndmask_b32_e32 v14, v15, v14, vcc
	v_div_scale_f32 v15, s[30:31], v14, v14, 1.0
	v_rcp_f32_e32 v216, v15
	v_div_scale_f32 v217, vcc, 1.0, v14, 1.0
	v_fma_f32 v218, -v15, v216, 1.0
	v_fmac_f32_e32 v216, v218, v216
	v_mul_f32_e32 v218, v217, v216
	v_fma_f32 v220, -v15, v218, v217
	v_fmac_f32_e32 v218, v220, v216
	v_fma_f32 v15, -v15, v218, v217
	v_div_fmas_f32 v15, v15, v216, v218
	v_div_fixup_f32 v14, v15, v14, 1.0
	s_mul_i32 s52, s9, 320
	s_lshl_b32 s53, s13, 5
	s_add_i32 s52, s52, s53
	s_add_i32 s52, s52, 0x800
	v_lshl_add_u32 v12, v13, 2, s52
	ds_write_b32 v12, v14
	s_nop 1
	v_readlane_b32 s20, v14, 0
	v_readlane_b32 s21, v14, 1
	v_readlane_b32 s22, v14, 2
	v_readlane_b32 s23, v14, 3
	v_readlane_b32 s24, v14, 4
	v_readlane_b32 s25, v14, 5
	v_readlane_b32 s26, v14, 6
	v_readlane_b32 s27, v14, 7
	s_lshl_b32 s53, s12, 2
	v_subrev_u32_e32 v216, s53, v12
	ds_read_b32 v217, v216
	v_add_u32_e32 v218, s15, v13
	v_cmp_le_u32_e32 vcc, s12, v218
	v_add_u32_e32 v218, 1, v218
	v_min_u32_e32 v218, s12, v218
	v_cvt_f32_u32_e32 v220, v218
	s_waitcnt lgkmcnt(0)
	v_cndmask_b32_e32 v217, 0, v217, vcc
	s_nop 1
	v_readlane_b32 s36, v217, 0
	v_readlane_b32 s37, v217, 1
	v_readlane_b32 s38, v217, 2
	v_readlane_b32 s39, v217, 3
	v_readlane_b32 s40, v217, 4
	v_readlane_b32 s41, v217, 5
	v_readlane_b32 s42, v217, 6
	v_readlane_b32 s43, v217, 7
	v_div_scale_f32 v15, s[30:31], v220, v220, 1.0
	v_rcp_f32_e32 v216, v15
	v_div_scale_f32 v217, vcc, 1.0, v220, 1.0
	v_fma_f32 v218, -v15, v216, 1.0
	v_fmac_f32_e32 v216, v218, v216
	v_mul_f32_e32 v218, v217, v216
	v_fma_f32 v221, -v15, v218, v217
	v_fmac_f32_e32 v218, v221, v216
	v_fma_f32 v15, -v15, v218, v217
	v_div_fmas_f32 v15, v15, v216, v218
	v_div_fixup_f32 v14, v15, v220, 1.0
	s_nop 1
	v_readlane_b32 s44, v14, 0
	v_readlane_b32 s45, v14, 1
	v_readlane_b32 s46, v14, 2
	v_readlane_b32 s47, v14, 3
	v_readlane_b32 s48, v14, 4
	v_readlane_b32 s49, v14, 5
	v_readlane_b32 s50, v14, 6
	v_readlane_b32 s51, v14, 7
	s_nop 1
	s_cmp_ge_u32 s13, 9
	s_cbranch_scc1 .Lp1f_nonext_m1
	s_add_i32 s55, s14, 8
	s_add_i32 s52, s55, 0
	s_mov_b32 s53, 0
	s_lshl_b64 s[52:53], s[52:53], 14
	s_add_u32 s52, s52, s2
	s_addc_u32 s53, s53, s3
	global_load_dwordx4 v[16:19], v1, s[52:53]
	global_load_dwordx4 v[20:23], v1, s[52:53] offset:1024
	s_add_i32 s52, s55, 1
	s_mov_b32 s53, 0
	s_lshl_b64 s[52:53], s[52:53], 14
	s_add_u32 s52, s52, s2
	s_addc_u32 s53, s53, s3
	global_load_dwordx4 v[24:27], v1, s[52:53]
	global_load_dwordx4 v[28:31], v1, s[52:53] offset:1024
	s_add_i32 s52, s55, 2
	s_mov_b32 s53, 0
	s_lshl_b64 s[52:53], s[52:53], 14
	s_add_u32 s52, s52, s2
	s_addc_u32 s53, s53, s3
	global_load_dwordx4 v[32:35], v1, s[52:53]
	global_load_dwordx4 v[36:39], v1, s[52:53] offset:1024
	s_add_i32 s52, s55, 3
	s_mov_b32 s53, 0
	s_lshl_b64 s[52:53], s[52:53], 14
	s_add_u32 s52, s52, s2
	s_addc_u32 s53, s53, s3
	global_load_dwordx4 v[40:43], v1, s[52:53]
	global_load_dwordx4 v[44:47], v1, s[52:53] offset:1024
	s_add_i32 s52, s55, 4
	s_mov_b32 s53, 0
	s_lshl_b64 s[52:53], s[52:53], 14
	s_add_u32 s52, s52, s2
	s_addc_u32 s53, s53, s3
	global_load_dwordx4 v[48:51], v1, s[52:53]
	global_load_dwordx4 v[52:55], v1, s[52:53] offset:1024
	s_add_i32 s52, s55, 5
	s_mov_b32 s53, 0
	s_lshl_b64 s[52:53], s[52:53], 14
	s_add_u32 s52, s52, s2
	s_addc_u32 s53, s53, s3
	global_load_dwordx4 v[56:59], v1, s[52:53]
	global_load_dwordx4 v[60:63], v1, s[52:53] offset:1024
	s_add_i32 s52, s55, 6
	s_mov_b32 s53, 0
	s_lshl_b64 s[52:53], s[52:53], 14
	s_add_u32 s52, s52, s2
	s_addc_u32 s53, s53, s3
	global_load_dwordx4 v[64:67], v1, s[52:53]
	global_load_dwordx4 v[68:71], v1, s[52:53] offset:1024
	s_add_i32 s52, s55, 7
	s_mov_b32 s53, 0
	s_lshl_b64 s[52:53], s[52:53], 14
	s_add_u32 s52, s52, s2
	s_addc_u32 s53, s53, s3
	global_load_dwordx4 v[72:75], v1, s[52:53]
	global_load_dwordx4 v[76:79], v1, s[52:53] offset:1024
